# attention: row-sum adds interleaved with the exps (separate accumulators), instead of a serial tail
# speedup vs baseline: 1.0103x; 1.0075x over previous
.LBB0_1102:
	v_add_f32_e32 v198, v200, v198
	v_add_f32_e32 v200, v80, v81
	v_add_f32_e32 v198, v200, v198
	v_add_f32_e32 v229, v229, v198
	s_add_i32 s9, s9, 1
	s_add_i32 s13, s13, 64
	s_add_i32 s22, s22, 64
	v_add_f32_e32 v231, v231, v199
	s_cmpk_eq_i32 s9, 0x84
	s_waitcnt lgkmcnt(0)
	s_barrier
	s_cbranch_scc1 .LBB0_1126

; #define MFMA32(a, b, c) __builtin_amdgcn_mfma_f32_32x32x16_bf16((a), (b), (c), 0, 0, 0)
; __device__ __forceinline__ void attn_unit2(const bf16_t* Qm, const bf16_t* KVm, const bf16_t* P1, bf16_t* OP, int q0, int h, int klat, int nlat, int kctx, int nt, uchar* lds, bool nostore = false) {
;     ...
;         SOFTMAX_BLK(sA0, sA1, mA, lA, oA0, oA1);
;         SOFTMAX_BLK(sB0, sB1, mB, lB, oB0, oB1);
;         const uchar* vb = Vt + buf * VT_BYTES + l32 * VROW + hi * 16;
; #pragma unroll
;         for (int kk = 0; kk < 4; ++kk) {
;             const int r0 = 8 * (kk & 1);
;             const bf16x8 pa = (kk >> 1) ? pack8(sA1[r0], sA1[r0 + 1], sA1[r0 + 2], sA1[r0 + 3], sA1[r0 + 4], sA1[r0 + 5], sA1[r0 + 6], sA1[r0 + 7])
;                                         : pack8(sA0[r0], sA0[r0 + 1], sA0[r0 + 2], sA0[r0 + 3], sA0[r0 + 4], sA0[r0 + 5], sA0[r0 + 6], sA0[r0 + 7]);
;             const bf16x8 pb = (kk >> 1) ? pack8(sB1[r0], sB1[r0 + 1], sB1[r0 + 2], sB1[r0 + 3], sB1[r0 + 4], sB1[r0 + 5], sB1[r0 + 6], sB1[r0 + 7])
;                                         : pack8(sB0[r0], sB0[r0 + 1], sB0[r0 + 2], sB0[r0 + 3], sB0[r0 + 4], sB0[r0 + 5], sB0[r0 + 6], sB0[r0 + 7]);
;             const bf16x8 a0 = *(const bf16x8*)(vb + kk * 32), a1 = *(const bf16x8*)(vb + 32 * VROW + kk * 32);
;             oA0 = MFMA32(a0, pa, oA0); oA1 = MFMA32(a1, pa, oA1); oB0 = MFMA32(a0, pb, oB0); oB1 = MFMA32(a1, pb, oB1);
;         }
.LBB0_1121:
	s_mul_i32 s5, s4, 0x2400
	v_add_u32_e32 v242, s5, v228
	ds_read_b128 v[212:215], v242 offset:26624
	ds_read_b128 v[238:241], v242 offset:31232
	v_exp_f32_e32 v100, v100
	v_exp_f32_e32 v101, v101
	v_exp_f32_e32 v102, v102
	v_add_f32_e32 v198, v100, v101
	v_exp_f32_e32 v103, v103
	v_exp_f32_e32 v0, v114
	v_add_f32_e32 v200, v102, v103
	v_exp_f32_e32 v114, v115
	v_add_f32_e32 v198, v200, v198
	v_exp_f32_e32 v115, v116
	v_add_f32_e32 v199, v0, v114
	v_exp_f32_e32 v116, v117
	v_exp_f32_e32 v117, v118
	v_add_f32_e32 v201, v115, v116
	v_exp_f32_e32 v118, v119
	v_add_f32_e32 v199, v201, v199
	v_exp_f32_e32 v119, v120
	v_add_f32_e32 v201, v117, v118
	v_exp_f32_e32 v120, v121
	v_add_f32_e32 v199, v201, v199
	v_exp_f32_e32 v104, v104
	v_add_f32_e32 v201, v119, v120
	v_exp_f32_e32 v98, v98
	v_add_f32_e32 v199, v201, v199
	v_exp_f32_e32 v105, v105
	v_add_f32_e32 v200, v104, v98
	v_cvt_pk_bf16_f32 v234, v0, v114
	v_cvt_pk_bf16_f32 v235, v115, v116
	v_cvt_pk_bf16_f32 v236, v117, v118
	v_cvt_pk_bf16_f32 v237, v119, v120
	v_exp_f32_e32 v121, v122
	v_add_f32_e32 v198, v200, v198
	s_waitcnt lgkmcnt(1)
	v_mfma_f32_32x32x16_bf16 v[50:65], v[212:215], v[234:237], v[50:65]
	v_exp_f32_e32 v122, v123
	v_exp_f32_e32 v123, v124
	v_add_f32_e32 v201, v121, v122
	v_exp_f32_e32 v124, v125
	v_add_f32_e32 v199, v201, v199
	v_exp_f32_e32 v125, v126
	v_add_f32_e32 v201, v123, v124
	v_exp_f32_e32 v126, v127
	v_add_f32_e32 v199, v201, v199
	v_exp_f32_e32 v127, v128
	v_add_f32_e32 v201, v125, v126
	v_exp_f32_e32 v128, v99
	v_add_f32_e32 v199, v201, v199
	v_exp_f32_e32 v99, v129
	v_add_f32_e32 v200, v105, v128
	s_waitcnt lgkmcnt(0)
	v_mfma_f32_32x32x16_bf16 v[34:49], v[238:241], v[234:237], v[34:49]
	v_cvt_pk_bf16_f32 v234, v98, v128
	v_cvt_pk_bf16_f32 v235, v100, v101
	v_cvt_pk_bf16_f32 v236, v102, v103
	v_cvt_pk_bf16_f32 v237, v104, v105
	s_nop 1
	v_mfma_f32_32x32x16_bf16 v[18:33], v[212:215], v[234:237], v[18:33]
	ds_read_b128 v[212:215], v242 offset:26656
	v_exp_f32_e32 v106, v106
	v_add_f32_e32 v198, v200, v198
	v_mfma_f32_32x32x16_bf16 v[2:17], v[238:241], v[234:237], v[2:17]
	ds_read_b128 v[238:241], v242 offset:31264
	v_exp_f32_e32 v107, v107
	v_add_f32_e32 v201, v127, v99
	v_exp_f32_e32 v108, v108
	v_add_f32_e32 v199, v201, v199
	v_exp_f32_e32 v109, v109
	v_add_f32_e32 v200, v106, v107
	v_exp_f32_e32 v110, v110
	v_add_f32_e32 v198, v200, v198
	v_exp_f32_e32 v111, v111
	v_add_f32_e32 v200, v108, v109
	v_exp_f32_e32 v112, v112
	v_add_f32_e32 v198, v200, v198
	v_exp_f32_e32 v113, v113
	v_add_f32_e32 v200, v110, v111
	v_cvt_pk_bf16_f32 v234, v121, v122
	v_cvt_pk_bf16_f32 v235, v123, v124
	v_cvt_pk_bf16_f32 v236, v125, v126
	v_cvt_pk_bf16_f32 v237, v127, v99
	v_exp_f32_e32 v129, v68
	v_add_f32_e32 v198, v200, v198
	s_waitcnt lgkmcnt(1)
	v_mfma_f32_32x32x16_bf16 v[50:65], v[212:215], v[234:237], v[50:65]
	v_exp_f32_e32 v69, v69
	v_add_f32_e32 v200, v112, v113
	v_exp_f32_e32 v70, v70
	v_add_f32_e32 v198, v200, v198
	s_waitcnt lgkmcnt(0)
	v_mfma_f32_32x32x16_bf16 v[34:49], v[238:241], v[234:237], v[34:49]
	v_cvt_pk_bf16_f32 v234, v106, v107
	v_cvt_pk_bf16_f32 v235, v108, v109
	v_cvt_pk_bf16_f32 v236, v110, v111
	v_cvt_pk_bf16_f32 v237, v112, v113
	s_nop 1
	v_mfma_f32_32x32x16_bf16 v[18:33], v[212:215], v[234:237], v[18:33]
	ds_read_b128 v[212:215], v242 offset:26688
	v_exp_f32_e32 v71, v71
	v_add_f32_e32 v200, v129, v69
	v_exp_f32_e32 v82, v82
	v_add_f32_e32 v198, v200, v198
	v_mfma_f32_32x32x16_bf16 v[2:17], v[238:241], v[234:237], v[2:17]
	ds_read_b128 v[238:241], v242 offset:31296
	v_exp_f32_e32 v83, v83
	v_add_f32_e32 v200, v70, v71
	v_exp_f32_e32 v84, v84
	v_add_f32_e32 v198, v200, v198
	v_exp_f32_e32 v85, v85
	v_add_f32_e32 v201, v82, v83
	v_exp_f32_e32 v86, v86
	v_add_f32_e32 v199, v201, v199
	v_exp_f32_e32 v87, v87
	v_add_f32_e32 v201, v84, v85
	v_exp_f32_e32 v88, v88
	v_add_f32_e32 v199, v201, v199
	v_exp_f32_e32 v89, v89
	v_add_f32_e32 v201, v86, v87
	v_exp_f32_e32 v72, v72
	v_add_f32_e32 v199, v201, v199
	v_exp_f32_e32 v66, v66
	v_add_f32_e32 v201, v88, v89
	v_exp_f32_e32 v67, v67
	v_add_f32_e32 v199, v201, v199
	v_exp_f32_e32 v73, v73
	v_add_f32_e32 v200, v72, v66
	v_cvt_pk_bf16_f32 v234, v82, v83
	v_cvt_pk_bf16_f32 v235, v84, v85
	v_cvt_pk_bf16_f32 v236, v86, v87
	v_cvt_pk_bf16_f32 v237, v88, v89
	s_waitcnt lgkmcnt(1)
	s_nop 0
	v_mfma_f32_32x32x16_bf16 v[50:65], v[212:215], v[234:237], v[50:65]
	v_exp_f32_e32 v90, v90
	v_add_f32_e32 v198, v200, v198
	s_waitcnt lgkmcnt(0)
	v_mfma_f32_32x32x16_bf16 v[34:49], v[238:241], v[234:237], v[34:49]
	v_cvt_pk_bf16_f32 v234, v66, v67
	v_cvt_pk_bf16_f32 v235, v129, v69
	v_cvt_pk_bf16_f32 v236, v70, v71
	v_cvt_pk_bf16_f32 v237, v72, v73
	v_exp_f32_e32 v91, v91
	v_add_f32_e32 v200, v67, v73
	v_exp_f32_e32 v92, v92
	v_add_f32_e32 v198, v200, v198
	v_exp_f32_e32 v93, v93
	v_add_f32_e32 v201, v90, v91
	v_mfma_f32_32x32x16_bf16 v[18:33], v[212:215], v[234:237], v[18:33]
	ds_read_b128 v[212:215], v242 offset:26720
	v_exp_f32_e32 v94, v94
	v_add_f32_e32 v199, v201, v199
	v_exp_f32_e32 v95, v95
	v_add_f32_e32 v201, v92, v93
	v_exp_f32_e32 v96, v96
	v_add_f32_e32 v199, v201, v199
	v_exp_f32_e32 v68, v97
	v_add_f32_e32 v201, v94, v95
	v_mfma_f32_32x32x16_bf16 v[2:17], v[238:241], v[234:237], v[2:17]
	ds_read_b128 v[238:241], v242 offset:31328
	v_exp_f32_e32 v74, v74
	v_add_f32_e32 v199, v201, v199
	v_exp_f32_e32 v75, v75
	v_add_f32_e32 v201, v96, v68
	v_exp_f32_e32 v76, v76
	v_add_f32_e32 v199, v201, v199
	v_exp_f32_e32 v77, v77
	v_add_f32_e32 v200, v74, v75
	v_exp_f32_e32 v78, v78
	v_add_f32_e32 v198, v200, v198
	v_exp_f32_e32 v79, v79
	v_add_f32_e32 v200, v76, v77
	v_exp_f32_e32 v80, v80
	v_add_f32_e32 v198, v200, v198
	v_exp_f32_e32 v81, v81
	v_add_f32_e32 v200, v78, v79
	v_cvt_pk_bf16_f32 v234, v90, v91
	v_cvt_pk_bf16_f32 v235, v92, v93
	v_cvt_pk_bf16_f32 v236, v94, v95
	v_cvt_pk_bf16_f32 v237, v96, v68
	s_andn2_b64 vcc, exec, s[44:45]
	s_waitcnt lgkmcnt(1)
	v_mfma_f32_32x32x16_bf16 v[50:65], v[212:215], v[234:237], v[50:65]
	s_waitcnt lgkmcnt(0)
	v_mfma_f32_32x32x16_bf16 v[34:49], v[238:241], v[234:237], v[34:49]
	v_cvt_pk_bf16_f32 v234, v74, v75
	v_cvt_pk_bf16_f32 v235, v76, v77
	v_cvt_pk_bf16_f32 v236, v78, v79
	v_cvt_pk_bf16_f32 v237, v80, v81
	s_nop 1
	v_mfma_f32_32x32x16_bf16 v[18:33], v[212:215], v[234:237], v[18:33]
	v_mfma_f32_32x32x16_bf16 v[2:17], v[238:241], v[234:237], v[2:17]
	s_cbranch_vccnz .LBB0_1102
	s_xor_b32 s7, s4, 1
	s_mul_i32 s4, s7, 0x3400
	s_add_i32 s6, s4, 0
	v_add3_u32 v97, s6, v222, v194
	s_waitcnt vmcnt(2)
	ds_write_b128 v97, v[178:181]
	s_and_saveexec_b64 s[4:5], s[40:41]
	s_xor_b64 s[4:5], exec, s[4:5]
	s_cbranch_execz .LBB0_1124
	s_mulk_i32 s7, 0x2400
	v_add_u32_e32 v97, s7, v230
	s_mov_b32 s18, 0x5040100
	s_mov_b32 s19, 0x7060302
	v_add_u32_e32 v97, 0x6800, v97
	s_waitcnt vmcnt(0)
	v_perm_b32 v212, v182, v186, s18
	v_perm_b32 v213, v182, v186, s19
	ds_write2_b32 v97, v212, v213 offset1:36
	v_perm_b32 v212, v183, v187, s18
	v_perm_b32 v213, v183, v187, s19
	ds_write2_b32 v97, v212, v213 offset0:72 offset1:108
	v_perm_b32 v212, v184, v188, s18
	v_perm_b32 v213, v184, v188, s19
	ds_write2_b32 v97, v212, v213 offset0:144 offset1:180
	v_perm_b32 v212, v185, v189, s18
	v_perm_b32 v213, v185, v189, s19
	ds_write2_b32 v97, v212, v213 offset0:216 offset1:252
